# P2 GEMM main loop: LDS half-tile image re-laid as 16 blocks of 8 rows x 128 B (XOR-swizzled 16-byte slots) so every LDS-DMA instruction fetches 8 whole 128-byte lines instead of 16 half lines
# speedup vs baseline: 1.0029x; 1.0029x over previous
; #define PG8_STAGE(bufoff, gbase, voff) do { _Pragma("unroll") for (int _i = 0; _i < 2; ++_i) \
;         __builtin_amdgcn_global_load_lds((const unsigned*)((const char*)(gbase) + (voff)[_i]), (PG8_LAS unsigned*)(lds + (bufoff) + ldsw + _i * 8192), 16, 0, 0); } while (0)
; template <class Epi, class Sched, bool ALIGN_EPI = false, bool SP2 = false>
; __device__ __forceinline__ void gemm_phase(PG8_LAS unsigned char* lds, const Gemm g, const Sched& S, const Epi& E) {
;     ...
;     for (int i = 0; i < 2; ++i) { int R, C; stage_rc(tid * 16 + i * 8192, R, C); const int Rb = Epi::PERM ? ((R & ~31) + perm32(R & 31)) : R;
;         voffA[i] = (unsigned)(R * K + C) * 2u; voffB[i] = (unsigned)(Rb * K + C) * 2u; }
;     ...
;     const char* cA = (const char*)g.A + (size_t)cur.pm * tstep; const char* cB = (const char*)g.Bt + (size_t)cur.pn * tstep;
;     S.a_ready(cur);
;     if constexpr (SP2) {
;         PG8_STAGE(PG8_SB(0, 0), cB, voffB); PG8_STAGE(PG8_SB(0, 1), cB + hstep, voffB); PG8_STAGE(PG8_SA(0, 0), cA, voffA); PG8_STAGE(PG8_SA(0, 1), cA + hstep, voffA);
.LBB0_287:
	v_ashrrev_i32_e32 v1, 31, v8
	v_lshrrev_b32_e32 v1, 26, v1
	v_add_u32_e32 v1, v8, v1
	v_ashrrev_i32_e32 v9, 6, v1
	v_bfe_i32 v1, v8, 27, 1
	v_lshlrev_b32_e32 v0, 4, v8
	v_lshrrev_b32_e32 v1, 22, v1
	v_add_u32_e32 v1, v0, v1
	v_and_b32_e32 v1, 0xfffffc00, v1
	v_sub_u32_e32 v1, v0, v1
	v_lshrrev_b32_e32 v2, 4, v1
	v_bitop3_b32 v2, v2, v1, 32 bitop3:0x6c
	v_ashrrev_i32_e32 v1, 31, v1
	v_lshrrev_b32_e32 v1, 26, v1
	v_lshlrev_b32_e32 v3, 3, v9
	v_add_u32_e32 v1, v2, v1
	v_and_b32_e32 v3, -16, v3
	v_ashrrev_i32_e32 v11, 6, v1
	v_add_u32_e32 v1, v11, v3
	v_lshlrev_b32_e32 v3, 5, v9
	s_ashr_i32 s0, s11, 3
	v_and_b32_e32 v10, 32, v3
	v_mul_i32_i24_e32 v3, 64, v11
	s_waitcnt lgkmcnt(0)
	s_add_u32 s41, s12, 0xb200000
	v_sub_u32_e32 v2, v2, v3
	v_mov_b32_e32 v3, 1
	s_addc_u32 s42, s13, 0
	v_ashrrev_i16_sdwa v2, v3, sext(v2) dst_sel:DWORD dst_unused:UNUSED_PAD src0_sel:DWORD src1_sel:BYTE_0
	v_lshlrev_b32_e32 v4, 1, v1
	v_lshrrev_b32_e32 v5, 2, v1
	v_and_b32_e32 v6, 3, v11
	s_mov_b32 s1, 0xffffe0
	s_add_u32 s43, s8, 0xc00000
	v_bfe_i32 v12, v2, 0, 16
	v_and_b32_e32 v4, 24, v4
	v_and_b32_e32 v5, 4, v5
	v_and_or_b32 v6, v1, s1, v6
	s_movk_i32 s8, 0xb00
	v_add_u32_e32 v2, v10, v12
	v_or3_b32 v4, v6, v5, v4
	v_mul_lo_u32 v1, v1, s8
	v_add_lshl_u32 v128, v2, v1, 1
	v_mul_u32_u24_e32 v1, 0xb00, v4
	v_add_u32_e32 v0, 0x2000, v0
	v_add_lshl_u32 v130, v1, v2, 1
	v_ashrrev_i32_e32 v1, 31, v0
	v_lshrrev_b32_e32 v1, 22, v1
	v_add_u32_e32 v1, v0, v1
	v_ashrrev_i32_e32 v13, 10, v1
	v_mul_i32_i24_e32 v1, 0x400, v13
	v_sub_u32_e32 v0, v0, v1
	v_lshrrev_b32_e32 v1, 4, v0
	v_bitop3_b32 v0, v1, v0, 32 bitop3:0x6c
	v_ashrrev_i32_e32 v2, 31, v0
	v_lshrrev_b32_e32 v2, 26, v2
	v_lshlrev_b32_e32 v1, 3, v13
	v_add_u32_e32 v2, v0, v2
	v_and_b32_e32 v1, -16, v1
	v_ashrrev_i32_e32 v14, 6, v2
	v_lshlrev_b32_e32 v4, 5, v13
	s_addc_u32 s47, s9, 0
	v_add_u32_e32 v1, v14, v1
	v_and_b32_e32 v15, 32, v4
	v_and_b32_e32 v4, 3, v14
	s_add_i32 s0, s16, s0
	v_and_or_b32 v4, v1, s1, v4
	s_ashr_i32 s1, s0, 31
	s_lshr_b32 s1, s1, 27
	s_add_i32 s1, s0, s1
	s_ashr_i32 s3, s1, 5
	s_andn2_b32 s1, s1, 31
	s_sub_i32 s0, s0, s1
	s_bfe_i32 s1, s0, 0x80000
	s_bfe_u32 s1, s1, 0x3000c
	s_add_i32 s1, s0, s1
	s_bfe_i32 s12, s1, 0x80000
	s_and_b32 s1, s1, 0xf8
	s_sub_i32 s0, s1, s0
	s_sext_i32_i16 s12, s12
	s_sext_i32_i8 s0, s0
	s_lshl_b32 s1, s3, 3
	s_ashr_i32 s9, s10, 6
	v_and_b32_e32 v2, 0xc0, v2
	s_lshr_b32 s18, s12, 3
	s_sub_i32 s0, s0, s1
	s_ashr_i32 s12, s12, 3
	v_sub_u32_e32 v0, v0, v2
	s_ashr_i32 s11, s10, 8
	s_lshl_b32 s52, s9, 10
	s_addk_i32 s0, 0x7f
	s_mul_hi_i32 s13, s12, 0x160000
	s_mul_i32 s12, s12, 0x160000
	v_ashrrev_i16_sdwa v0, v3, sext(v0) dst_sel:DWORD dst_unused:UNUSED_PAD src0_sel:DWORD src1_sel:BYTE_0
	v_lshlrev_b32_e32 v2, 1, v1
	v_lshrrev_b32_e32 v3, 2, v1
	s_add_u32 s34, s43, s12
	v_bfe_i32 v16, v0, 0, 16
	v_and_b32_e32 v2, 24, v2
	v_and_b32_e32 v3, 4, v3
	s_addc_u32 s35, s47, s13
	s_add_i32 s53, s52, 0
	v_add_u32_e32 v0, v15, v16
	v_or3_b32 v2, v4, v3, v2
	v_mul_lo_u32 v1, v1, s8
	s_add_i32 m0, s53, 0x10000
	v_add_lshl_u32 v132, v0, v1, 1
	v_mul_u32_u24_e32 v1, 0xb00, v2
	v_bfe_u32 v239, v8, 3, 3
	v_and_b32_e32 v240, 7, v8
	v_xor_b32_e32 v240, v240, v239
	v_lshlrev_b32_e32 v240, 4, v240
	v_lshrrev_b32_e32 v241, 6, v8
	v_lshl_add_u32 v242, v241, 3, v239
	v_mov_b32_e32 v243, 0x1600
	v_mad_u32_u24 v128, v242, v243, v240
	v_add_u32_e32 v132, 0x58000, v128
	v_lshrrev_b32_e32 v244, 2, v241
	v_lshlrev_b32_e32 v244, 5, v244
	v_and_b32_e32 v245, 1, v241
	v_lshrrev_b32_e32 v246, 2, v239
	v_lshl_add_u32 v245, v245, 1, v246
	v_lshl_add_u32 v244, v245, 3, v244
	v_bfe_u32 v245, v241, 1, 1
	v_lshl_add_u32 v244, v245, 2, v244
	v_and_b32_e32 v245, 3, v239
	v_add_u32_e32 v244, v244, v245
	v_mad_u32_u24 v130, v244, v243, v240
	v_add_u32_e32 v134, 0x58000, v130
	global_load_lds_dwordx4 v130, s[34:35]
	s_add_i32 m0, s53, 0x12000
	s_add_u32 s12, s34, 0xb0000
	global_load_lds_dwordx4 v134, s[34:35]
	s_addc_u32 s13, s35, 0
	s_add_i32 m0, s53, 0x14000
	s_mul_i32 s3, s0, 0x160000
	global_load_lds_dwordx4 v130, s[12:13]
	s_add_i32 m0, s53, 0x16000
	s_mul_hi_u32 s1, s0, 0x160000
	s_add_u32 s30, s41, s3
	s_addc_u32 s31, s42, s1
	s_add_i32 s54, s53, 0x2000
	global_load_lds_dwordx4 v134, s[12:13]
	s_mov_b32 m0, s53
	s_add_u32 s12, s30, 0xb0000
	global_load_lds_dwordx4 v128, s[30:31]
	s_mov_b32 m0, s54
	s_addc_u32 s13, s31, 0
	s_add_i32 s55, s53, 0x4000
	global_load_lds_dwordx4 v132, s[30:31]
	s_mov_b32 m0, s55
	s_add_i32 s56, s53, 0x6000
	global_load_lds_dwordx4 v128, s[12:13]
	s_mov_b32 m0, s56
	v_mov_b32_e32 v131, 0
	global_load_lds_dwordx4 v132, s[12:13]
	v_mov_b32_e32 v135, v131
	v_mov_b32_e32 v129, v131
	v_mov_b32_e32 v133, v131
	s_cmp_eq_u32 s11, 1
	s_mov_b32 s57, 0
	v_lshl_add_u64 v[6:7], s[34:35], 0, v[130:131]
	v_lshl_add_u64 v[4:5], s[34:35], 0, v[134:135]
	v_lshl_add_u64 v[0:1], s[30:31], 0, v[128:129]
	s_cselect_b64 s[12:13], -1, 0
	s_cmp_lg_u32 s11, 1
	v_lshl_add_u64 v[2:3], s[30:31], 0, v[132:133]
	s_cbranch_scc1 .LBB0_289
	s_barrier
; #define PG8_STAGE(bufoff, gbase, voff) do { _Pragma("unroll") for (int _i = 0; _i < 2; ++_i) \
;         __builtin_amdgcn_global_load_lds((const unsigned*)((const char*)(gbase) + (voff)[_i]), (PG8_LAS unsigned*)(lds + (bufoff) + ldsw + _i * 8192), 16, 0, 0); } while (0)
; #define PG8_WAIT_V(n) asm volatile("s_waitcnt vmcnt(" #n ")" ::: "memory")
; #define PG8_BAR __builtin_amdgcn_s_barrier()
; template <class Epi, class Sched, bool ALIGN_EPI = false, bool SP2 = false>
; __device__ __forceinline__ void gemm_phase(PG8_LAS unsigned char* lds, const Gemm g, const Sched& S, const Epi& E) {
;     ...
;     const unsigned ldsw = (unsigned)wid * 1024u;
;     const int aoff = lds_byte(wr * 64 + fr, fq * 8), boff = lds_byte(wc * 32 + fr, fq * 8);
;     ...
;         PG8_STAGE(PG8_SB(1, 0), cB + kstep, voffB); PG8_STAGE(PG8_SA(1, 0), cA + kstep, voffA); PG8_STAGE(PG8_SB(1, 1), cB + hstep + kstep, voffB);
;         PG8_WAIT_V(6); PG8_BAR;
.LBB0_289:
	s_add_u32 s14, s6, 0x7100000
	s_addc_u32 s15, s7, 0
	s_lshl_b32 s1, s9, 5
	s_mov_b64 s[16:17], 0x80
	s_and_b32 s9, s1, 0x60
	s_add_i32 m0, s53, 0x18000
	v_lshl_add_u64 v[6:7], v[6:7], 0, s[16:17]
	s_lshl_b32 s3, s11, 13
	s_lshl_b32 s19, s9, 7
	s_waitcnt vmcnt(2)
	s_barrier
	global_load_lds_dwordx4 v[6:7], off
	v_lshl_add_u64 v[4:5], v[4:5], 0, s[16:17]
	s_add_i32 m0, s53, 0x1a000
	s_add_i32 s58, s53, 0x8000
	s_add_i32 s59, s53, 0xa000
	global_load_lds_dwordx4 v[4:5], off
	v_lshl_add_u64 v[0:1], v[0:1], 0, s[16:17]
	s_mov_b32 m0, s58
	s_add_u32 s6, s34, 0xb0080
	global_load_lds_dwordx4 v[0:1], off
	v_lshl_add_u64 v[0:1], v[2:3], 0, s[16:17]
	s_mov_b32 m0, s59
	s_addc_u32 s7, s35, 0
	global_load_lds_dwordx4 v[0:1], off
	s_add_i32 m0, s53, 0x1c000
	v_lshl_add_u64 v[0:1], s[6:7], 0, v[130:131]
	global_load_lds_dwordx4 v[0:1], off
	v_lshl_add_u64 v[0:1], s[6:7], 0, v[134:135]
	s_add_i32 m0, s53, 0x1e000
	s_cmpk_lt_u32 s10, 0x100
	global_load_lds_dwordx4 v[0:1], off
	v_lshrrev_b32_e32 v1, 1, v8
	v_and_b32_e32 v1, 24, v1
	v_and_b32_e32 v0, 15, v8
	v_lshlrev_b32_e32 v2, 1, v1
	v_lshl_or_b32 v144, s11, 6, v0
	v_lshl_or_b32 v0, v0, 6, v2
	v_lshlrev_b32_e32 v2, 2, v8
	v_and_b32_e32 v2, 32, v2
	v_bitop3_b32 v3, v0, s3, v2 bitop3:0xde
	v_bitop3_b32 v145, v0, s19, v2 bitop3:0xde
	v_and_b32_e32 v239, 15, v8
	v_and_b32_e32 v240, 7, v239
	v_lshrrev_b32_e32 v239, 3, v239
	v_lshlrev_b32_e32 v239, 10, v239
	v_lshl_add_u32 v239, v240, 7, v239
	v_bfe_u32 v241, v8, 4, 2
	v_xor_b32_e32 v242, v241, v240
	v_or_b32_e32 v241, 4, v241
	v_xor_b32_e32 v243, v241, v240
	v_lshl_add_u32 v242, v242, 4, v239
	v_lshl_add_u32 v243, v243, 4, v239
	v_lshrrev_b32_e32 v244, 8, v8
	v_lshlrev_b32_e32 v244, 13, v244
	v_add_u32_e32 v3, v244, v242
	v_add_u32_e32 v233, v244, v243
	v_bfe_u32 v244, v8, 6, 2
	v_lshlrev_b32_e32 v244, 12, v244
	v_add_u32_e32 v145, v244, v242
	v_add_u32_e32 v234, v244, v243
	v_or_b32_e32 v146, s9, v1
	v_lshrrev_b32_e32 v1, 1, v9
	v_mul_lo_u32 v0, v11, s8
	s_mov_b32 s3, 0xb000
	v_mad_u64_u32 v[0:1], s[10:11], v1, s3, v[0:1]
	v_or_b32_e32 v0, v0, v10
	s_mov_b64 s[6:7], 0xb0080
	v_add_lshl_u32 v0, v0, v12, 1
	v_mov_b32_e32 v1, v131
	v_lshl_add_u64 v[136:137], v[0:1], 0, s[6:7]
	v_add_u32_e32 v136, 0xb0080, v128
	v_mov_b32_e32 v137, 0
	v_lshrrev_b32_e32 v1, 1, v13
	v_mul_lo_u32 v0, v14, s8
	v_mad_u64_u32 v[0:1], s[8:9], v1, s3, v[0:1]
	s_waitcnt vmcnt(6)
	v_or_b32_e32 v0, v0, v15
	s_sext_i32_i8 s1, s18
	s_cselect_b64 s[18:19], -1, 0
	v_add_lshl_u32 v0, v0, v16, 1
	v_mov_b32_e32 v1, v131
	s_add_i32 s62, 0, 0x10000
	s_add_i32 s63, 0, 0x14000
	s_ashr_i32 s60, s94, 31
	s_mov_b32 s61, s94
	v_lshl_add_u64 v[138:139], v[0:1], 0, s[6:7]
	v_add_u32_e32 v138, 0xb0080, v132
	v_mov_b32_e32 v139, 0
	v_mov_b64_e32 v[140:141], 0x200
	v_mov_b64_e32 v[142:143], 0x1ff
	v_add_u32_e32 v147, s62, v145
	v_add_u32_e32 v235, s62, v234
	v_add_u32_e32 v148, s63, v145
	v_add_u32_e32 v236, s63, v234
	v_add_u32_e32 v149, 0, v3
	s_mov_b64 s[20:21], 0x40000
	s_mov_b32 s64, 0x40000
	s_mov_b64 s[22:23], 0x48000
	s_mov_b32 s65, 0x48000
	s_mov_b64 s[24:25], 0x50000
	s_mov_b32 s66, 0x50000
	s_mov_b64 s[26:27], 0x58000
	s_mov_b32 s67, 0x58000
	s_barrier
	s_branch .LBB0_292

; #define PG8_STAGE(bufoff, gbase, voff) do { _Pragma("unroll") for (int _i = 0; _i < 2; ++_i) \
;         __builtin_amdgcn_global_load_lds((const unsigned*)((const char*)(gbase) + (voff)[_i]), (PG8_LAS unsigned*)(lds + (bufoff) + ldsw + _i * 8192), 16, 0, 0); } while (0)
; #define PG8_LDA(dst, b, h) do { _Pragma("unroll") for (int m = 0; m < 4; ++m) _Pragma("unroll") for (int k = 0; k < 2; ++k) dst[m][k] = *(const PG8_LAS bf16x8*)(lds + PG8_SA(b, h) + aoff + m * 2048 + k * 1024); } while (0)
; #define PG8_LDB(dst, b, h) do { _Pragma("unroll") for (int n = 0; n < 2; ++n) _Pragma("unroll") for (int k = 0; k < 2; ++k) dst[n][k] = *(const PG8_LAS bf16x8*)(lds + PG8_SB(b, h) + boff + n * 2048 + k * 1024); } while (0)
; #define PG8_MMA(ai, bj, At, Bt) do { __builtin_amdgcn_s_setprio(1); _Pragma("unroll") for (int m = 0; m < 4; ++m) _Pragma("unroll") for (int n = 0; n < 2; ++n) _Pragma("unroll") for (int k = 0; k < 2; ++k) \
;         acc[ai][bj][m][n] = __builtin_amdgcn_mfma_f32_16x16x32_bf16(Bt[n][k], At[m][k], acc[ai][bj][m][n], 0, 0, 0); __builtin_amdgcn_s_setprio(0); } while (0)
; #define PG8_WAIT_V(n) asm volatile("s_waitcnt vmcnt(" #n ")" ::: "memory")
; #define PG8_WAIT_L(n) asm volatile("s_waitcnt lgkmcnt(" #n ")" ::: "memory")
; #define PG8_BAR __builtin_amdgcn_s_barrier()
; #define PG8_SCHED __builtin_amdgcn_sched_barrier(0)
; template <class Epi, class Sched, bool ALIGN_EPI = false, bool SP2 = false>
; __device__ __forceinline__ void gemm_phase(PG8_LAS unsigned char* lds, const Gemm g, const Sched& S, const Epi& E) {
;     ...
;             PG8_LDB(B0, 0, 0); PG8_LDB(B1, 0, 1); PG8_SCHED; PG8_LDA(At, 0, 0); PG8_STAGE(PG8_SA(1, 1), a1 + hstep, voffA);
;             PG8_WAIT_V(8); PG8_WAIT_L(0); PG8_BAR; PG8_MMA(0, 0, At, B0); PG8_MMA(0, 1, At, B1); PG8_BAR; PG8_SCHED;
;             PG8_LDA(At, 0, 1); PG8_STAGE(PG8_SB(0, 0), b2, voffB); PG8_STAGE(PG8_SB(0, 1), b2 + hstep, voffB); PG8_STAGE(PG8_SA(0, 0), a2, voffA);
.LBB0_303:
	ds_read_b128 v[150:153], v147
	ds_read_b128 v[154:157], v235
	ds_read_b128 v[158:161], v147 offset:2048
	ds_read_b128 v[162:165], v235 offset:2048
	ds_read_b128 v[166:169], v148
	ds_read_b128 v[170:173], v236
	ds_read_b128 v[174:177], v148 offset:2048
	ds_read_b128 v[178:181], v236 offset:2048
	s_add_u32 s34, s30, 0x100
	s_addc_u32 s35, s31, 0
	s_cmp_eq_u32 s74, 40
	s_cselect_b32 s39, s9, s35
	s_cselect_b32 s38, s8, s34
	s_cselect_b32 s37, s29, s73
	s_cselect_b32 s36, s28, s72
	v_lshl_add_u64 v[222:223], s[30:31], 0, v[136:137]
	s_add_i32 m0, s53, 0xc000
	ds_read_b128 v[190:193], v149
	ds_read_b128 v[194:197], v233
	ds_read_b128 v[198:201], v149 offset:2048
	ds_read_b128 v[202:205], v233 offset:2048
	ds_read_b128 v[206:209], v149 offset:4096
	ds_read_b128 v[210:213], v233 offset:4096
	ds_read_b128 v[214:217], v149 offset:6144
	ds_read_b128 v[218:221], v233 offset:6144
	global_load_lds_dwordx4 v[222:223], off
	v_lshl_add_u64 v[222:223], s[30:31], 0, v[138:139]
	s_add_i32 m0, s53, 0xe000
	s_nop 0
	global_load_lds_dwordx4 v[222:223], off
	s_waitcnt vmcnt(8)
	s_waitcnt lgkmcnt(0)
	s_barrier
	s_setprio 1
	s_waitcnt lgkmcnt(0)
	v_mfma_f32_16x16x32_bf16 v[124:127], v[150:153], v[190:193], v[124:127]
	v_mfma_f32_16x16x32_bf16 v[120:123], v[158:161], v[190:193], v[120:123]
	v_mfma_f32_16x16x32_bf16 v[116:119], v[150:153], v[198:201], v[116:119]
	v_mfma_f32_16x16x32_bf16 v[112:115], v[158:161], v[198:201], v[112:115]
	v_mfma_f32_16x16x32_bf16 v[108:111], v[150:153], v[206:209], v[108:111]
	v_mfma_f32_16x16x32_bf16 v[104:107], v[158:161], v[206:209], v[104:107]
	v_mfma_f32_16x16x32_bf16 v[100:103], v[150:153], v[214:217], v[100:103]
	v_mfma_f32_16x16x32_bf16 v[96:99], v[158:161], v[214:217], v[96:99]
	v_mfma_f32_16x16x32_bf16 v[124:127], v[154:157], v[194:197], v[124:127]
	v_mfma_f32_16x16x32_bf16 v[120:123], v[162:165], v[194:197], v[120:123]
	v_mfma_f32_16x16x32_bf16 v[116:119], v[154:157], v[202:205], v[116:119]
	v_mfma_f32_16x16x32_bf16 v[112:115], v[162:165], v[202:205], v[112:115]
	v_mfma_f32_16x16x32_bf16 v[108:111], v[154:157], v[210:213], v[108:111]
	v_mfma_f32_16x16x32_bf16 v[104:107], v[162:165], v[210:213], v[104:107]
	v_mfma_f32_16x16x32_bf16 v[100:103], v[154:157], v[218:221], v[100:103]
	v_mfma_f32_16x16x32_bf16 v[96:99], v[162:165], v[218:221], v[96:99]
	s_setprio 0
	s_setprio 1
	v_mfma_f32_16x16x32_bf16 v[76:79], v[166:169], v[190:193], v[76:79]
	v_mfma_f32_16x16x32_bf16 v[68:71], v[174:177], v[190:193], v[68:71]
	v_mfma_f32_16x16x32_bf16 v[60:63], v[166:169], v[198:201], v[60:63]
	v_mfma_f32_16x16x32_bf16 v[52:55], v[174:177], v[198:201], v[52:55]
	v_mfma_f32_16x16x32_bf16 v[44:47], v[166:169], v[206:209], v[44:47]
	v_mfma_f32_16x16x32_bf16 v[40:43], v[174:177], v[206:209], v[40:43]
	v_mfma_f32_16x16x32_bf16 v[36:39], v[166:169], v[214:217], v[36:39]
	v_mfma_f32_16x16x32_bf16 v[32:35], v[174:177], v[214:217], v[32:35]
	v_mfma_f32_16x16x32_bf16 v[76:79], v[170:173], v[194:197], v[76:79]
	v_mfma_f32_16x16x32_bf16 v[68:71], v[178:181], v[194:197], v[68:71]
	v_mfma_f32_16x16x32_bf16 v[60:63], v[170:173], v[202:205], v[60:63]
	v_mfma_f32_16x16x32_bf16 v[52:55], v[178:181], v[202:205], v[52:55]
	v_mfma_f32_16x16x32_bf16 v[44:47], v[170:173], v[210:213], v[44:47]
	v_mfma_f32_16x16x32_bf16 v[40:43], v[178:181], v[210:213], v[40:43]
	v_mfma_f32_16x16x32_bf16 v[36:39], v[170:173], v[218:221], v[36:39]
	v_mfma_f32_16x16x32_bf16 v[32:35], v[178:181], v[218:221], v[32:35]
	s_setprio 0
	s_barrier
	s_add_i32 s3, s62, s52
	v_lshl_add_u64 v[222:223], s[36:37], 0, v[130:131]
	s_mov_b32 m0, s3
	ds_read_b128 v[190:193], v149 offset:16384
	ds_read_b128 v[194:197], v233 offset:16384
	ds_read_b128 v[198:201], v149 offset:18432
	ds_read_b128 v[202:205], v233 offset:18432
	ds_read_b128 v[206:209], v149 offset:20480
	ds_read_b128 v[210:213], v233 offset:20480
	ds_read_b128 v[214:217], v149 offset:22528
	ds_read_b128 v[218:221], v233 offset:22528
	global_load_lds_dwordx4 v[222:223], off
	s_add_i32 m0, s3, 0x2000
	s_add_u32 s10, s36, 0xb0000
	v_lshl_add_u64 v[224:225], s[36:37], 0, v[134:135]
	s_addc_u32 s11, s37, 0
	s_add_i32 s3, s63, s52
	global_load_lds_dwordx4 v[224:225], off
	v_lshl_add_u64 v[226:227], s[10:11], 0, v[130:131]
	s_mov_b32 m0, s3
	v_lshl_add_u64 v[228:229], s[38:39], 0, v[132:133]
	global_load_lds_dwordx4 v[226:227], off
	v_lshl_add_u64 v[226:227], s[10:11], 0, v[134:135]
	s_add_i32 m0, s3, 0x2000
	s_nop 0
	global_load_lds_dwordx4 v[226:227], off
	v_lshl_add_u64 v[226:227], s[38:39], 0, v[128:129]
	s_mov_b32 m0, s53
	s_nop 0
	global_load_lds_dwordx4 v[226:227], off
	s_mov_b32 m0, s54
	s_nop 0
	global_load_lds_dwordx4 v[228:229], off
	s_waitcnt vmcnt(8)
	s_waitcnt lgkmcnt(0)
	s_barrier
; #define PG8_STAGE(bufoff, gbase, voff) do { _Pragma("unroll") for (int _i = 0; _i < 2; ++_i) \
;         __builtin_amdgcn_global_load_lds((const unsigned*)((const char*)(gbase) + (voff)[_i]), (PG8_LAS unsigned*)(lds + (bufoff) + ldsw + _i * 8192), 16, 0, 0); } while (0)
; #define PG8_LDA(dst, b, h) do { _Pragma("unroll") for (int m = 0; m < 4; ++m) _Pragma("unroll") for (int k = 0; k < 2; ++k) dst[m][k] = *(const PG8_LAS bf16x8*)(lds + PG8_SA(b, h) + aoff + m * 2048 + k * 1024); } while (0)
; #define PG8_LDB(dst, b, h) do { _Pragma("unroll") for (int n = 0; n < 2; ++n) _Pragma("unroll") for (int k = 0; k < 2; ++k) dst[n][k] = *(const PG8_LAS bf16x8*)(lds + PG8_SB(b, h) + boff + n * 2048 + k * 1024); } while (0)
; #define PG8_MMA(ai, bj, At, Bt) do { __builtin_amdgcn_s_setprio(1); _Pragma("unroll") for (int m = 0; m < 4; ++m) _Pragma("unroll") for (int n = 0; n < 2; ++n) _Pragma("unroll") for (int k = 0; k < 2; ++k) \
;         acc[ai][bj][m][n] = __builtin_amdgcn_mfma_f32_16x16x32_bf16(Bt[n][k], At[m][k], acc[ai][bj][m][n], 0, 0, 0); __builtin_amdgcn_s_setprio(0); } while (0)
; #define PG8_WAIT_V(n) asm volatile("s_waitcnt vmcnt(" #n ")" ::: "memory")
; #define PG8_WAIT_L(n) asm volatile("s_waitcnt lgkmcnt(" #n ")" ::: "memory")
; #define PG8_BAR __builtin_amdgcn_s_barrier()
; #define PG8_SCHED __builtin_amdgcn_sched_barrier(0)
; template <class Epi, class Sched, bool ALIGN_EPI = false, bool SP2 = false>
; __device__ __forceinline__ void gemm_phase(PG8_LAS unsigned char* lds, const Gemm g, const Sched& S, const Epi& E) {
;     ...
;             PG8_WAIT_V(8); PG8_WAIT_L(0); PG8_BAR; PG8_MMA(1, 0, At, B0); PG8_MMA(1, 1, At, B1); PG8_BAR; PG8_SCHED;
;             PG8_LDB(B0, 1, 0); PG8_LDB(B1, 1, 1); PG8_SCHED; PG8_LDA(At, 1, 0); PG8_STAGE(PG8_SA(0, 1), a2 + hstep, voffA);
;             PG8_WAIT_V(8); PG8_WAIT_L(0); PG8_BAR; PG8_MMA(0, 0, At, B0); PG8_MMA(0, 1, At, B1); PG8_BAR; PG8_SCHED;
	s_setprio 1
	s_waitcnt lgkmcnt(0)
	v_mfma_f32_16x16x32_bf16 v[92:95], v[150:153], v[190:193], v[92:95]
	v_mfma_f32_16x16x32_bf16 v[88:91], v[158:161], v[190:193], v[88:91]
	v_mfma_f32_16x16x32_bf16 v[84:87], v[150:153], v[198:201], v[84:87]
	v_mfma_f32_16x16x32_bf16 v[80:83], v[158:161], v[198:201], v[80:83]
	v_mfma_f32_16x16x32_bf16 v[72:75], v[150:153], v[206:209], v[72:75]
	v_mfma_f32_16x16x32_bf16 v[64:67], v[158:161], v[206:209], v[64:67]
	v_mfma_f32_16x16x32_bf16 v[56:59], v[150:153], v[214:217], v[56:59]
	v_mfma_f32_16x16x32_bf16 v[48:51], v[158:161], v[214:217], v[48:51]
	v_mfma_f32_16x16x32_bf16 v[92:95], v[154:157], v[194:197], v[92:95]
	v_mfma_f32_16x16x32_bf16 v[88:91], v[162:165], v[194:197], v[88:91]
	v_mfma_f32_16x16x32_bf16 v[84:87], v[154:157], v[202:205], v[84:87]
	v_mfma_f32_16x16x32_bf16 v[80:83], v[162:165], v[202:205], v[80:83]
	v_mfma_f32_16x16x32_bf16 v[72:75], v[154:157], v[210:213], v[72:75]
	v_mfma_f32_16x16x32_bf16 v[64:67], v[162:165], v[210:213], v[64:67]
	v_mfma_f32_16x16x32_bf16 v[56:59], v[154:157], v[218:221], v[56:59]
	v_mfma_f32_16x16x32_bf16 v[48:51], v[162:165], v[218:221], v[48:51]
	s_setprio 0
	s_setprio 1
	v_mfma_f32_16x16x32_bf16 v[28:31], v[166:169], v[190:193], v[28:31]
	v_mfma_f32_16x16x32_bf16 v[24:27], v[174:177], v[190:193], v[24:27]
	v_mfma_f32_16x16x32_bf16 v[20:23], v[166:169], v[198:201], v[20:23]
	v_mfma_f32_16x16x32_bf16 v[16:19], v[174:177], v[198:201], v[16:19]
	v_mfma_f32_16x16x32_bf16 v[12:15], v[166:169], v[206:209], v[12:15]
	v_mfma_f32_16x16x32_bf16 v[8:11], v[174:177], v[206:209], v[8:11]
	v_mfma_f32_16x16x32_bf16 v[4:7], v[166:169], v[214:217], v[4:7]
	v_mfma_f32_16x16x32_bf16 v[0:3], v[174:177], v[214:217], v[0:3]
	v_mfma_f32_16x16x32_bf16 v[28:31], v[170:173], v[194:197], v[28:31]
	v_mfma_f32_16x16x32_bf16 v[24:27], v[178:181], v[194:197], v[24:27]
	v_mfma_f32_16x16x32_bf16 v[20:23], v[170:173], v[202:205], v[20:23]
	v_mfma_f32_16x16x32_bf16 v[16:19], v[178:181], v[202:205], v[16:19]
	v_mfma_f32_16x16x32_bf16 v[12:15], v[170:173], v[210:213], v[12:15]
	v_mfma_f32_16x16x32_bf16 v[8:11], v[178:181], v[210:213], v[8:11]
	v_mfma_f32_16x16x32_bf16 v[4:7], v[170:173], v[218:221], v[4:7]
	v_mfma_f32_16x16x32_bf16 v[0:3], v[178:181], v[218:221], v[0:3]
	s_setprio 0
	s_barrier
	s_add_i32 s3, 0, 0x18000
	s_add_i32 s30, 0, 0x1c000
	v_add_u32_e32 v162, s3, v145
	v_add_u32_e32 v237, s3, v234
	v_add_u32_e32 v178, s30, v145
	v_add_u32_e32 v238, s30, v234
	ds_read_b128 v[150:153], v162
	ds_read_b128 v[154:157], v237
	ds_read_b128 v[158:161], v162 offset:2048
	ds_read_b128 v[162:165], v237 offset:2048
	ds_read_b128 v[166:169], v178
	ds_read_b128 v[170:173], v238
	ds_read_b128 v[174:177], v178 offset:2048
	ds_read_b128 v[178:181], v238 offset:2048
	s_add_u32 s10, s38, 0xb0000
	s_addc_u32 s11, s39, 0
	s_mov_b32 m0, s55
	v_lshl_add_u64 v[230:231], s[10:11], 0, v[128:129]
	ds_read_b128 v[190:193], v149 offset:32768
	ds_read_b128 v[194:197], v233 offset:32768
	ds_read_b128 v[198:201], v149 offset:34816
	ds_read_b128 v[202:205], v233 offset:34816
	ds_read_b128 v[206:209], v149 offset:36864
	ds_read_b128 v[210:213], v233 offset:36864
	ds_read_b128 v[214:217], v149 offset:38912
	ds_read_b128 v[218:221], v233 offset:38912
	global_load_lds_dwordx4 v[230:231], off
	v_lshl_add_u64 v[230:231], s[10:11], 0, v[132:133]
	s_mov_b32 m0, s56
	s_nop 0
	global_load_lds_dwordx4 v[230:231], off
	s_waitcnt vmcnt(8)
	s_waitcnt lgkmcnt(0)
	s_barrier
	s_setprio 1
	s_waitcnt lgkmcnt(0)
	v_mfma_f32_16x16x32_bf16 v[124:127], v[150:153], v[190:193], v[124:127]
	v_mfma_f32_16x16x32_bf16 v[120:123], v[158:161], v[190:193], v[120:123]
	v_mfma_f32_16x16x32_bf16 v[116:119], v[150:153], v[198:201], v[116:119]
	v_mfma_f32_16x16x32_bf16 v[112:115], v[158:161], v[198:201], v[112:115]
	v_mfma_f32_16x16x32_bf16 v[108:111], v[150:153], v[206:209], v[108:111]
	v_mfma_f32_16x16x32_bf16 v[104:107], v[158:161], v[206:209], v[104:107]
	v_mfma_f32_16x16x32_bf16 v[100:103], v[150:153], v[214:217], v[100:103]
	v_mfma_f32_16x16x32_bf16 v[96:99], v[158:161], v[214:217], v[96:99]
	v_mfma_f32_16x16x32_bf16 v[124:127], v[154:157], v[194:197], v[124:127]
	v_mfma_f32_16x16x32_bf16 v[120:123], v[162:165], v[194:197], v[120:123]
	v_mfma_f32_16x16x32_bf16 v[116:119], v[154:157], v[202:205], v[116:119]
	v_mfma_f32_16x16x32_bf16 v[112:115], v[162:165], v[202:205], v[112:115]
	v_mfma_f32_16x16x32_bf16 v[108:111], v[154:157], v[210:213], v[108:111]
	v_mfma_f32_16x16x32_bf16 v[104:107], v[162:165], v[210:213], v[104:107]
	v_mfma_f32_16x16x32_bf16 v[100:103], v[154:157], v[218:221], v[100:103]
	v_mfma_f32_16x16x32_bf16 v[96:99], v[162:165], v[218:221], v[96:99]
	s_setprio 0
	s_setprio 1
	v_mfma_f32_16x16x32_bf16 v[76:79], v[166:169], v[190:193], v[76:79]
	v_mfma_f32_16x16x32_bf16 v[68:71], v[174:177], v[190:193], v[68:71]
	v_mfma_f32_16x16x32_bf16 v[60:63], v[166:169], v[198:201], v[60:63]
	v_mfma_f32_16x16x32_bf16 v[52:55], v[174:177], v[198:201], v[52:55]
	v_mfma_f32_16x16x32_bf16 v[44:47], v[166:169], v[206:209], v[44:47]
	v_mfma_f32_16x16x32_bf16 v[40:43], v[174:177], v[206:209], v[40:43]
	v_mfma_f32_16x16x32_bf16 v[36:39], v[166:169], v[214:217], v[36:39]
	v_mfma_f32_16x16x32_bf16 v[32:35], v[174:177], v[214:217], v[32:35]
	v_mfma_f32_16x16x32_bf16 v[76:79], v[170:173], v[194:197], v[76:79]
	v_mfma_f32_16x16x32_bf16 v[68:71], v[178:181], v[194:197], v[68:71]
	v_mfma_f32_16x16x32_bf16 v[60:63], v[170:173], v[202:205], v[60:63]
	v_mfma_f32_16x16x32_bf16 v[52:55], v[178:181], v[202:205], v[52:55]
	v_mfma_f32_16x16x32_bf16 v[44:47], v[170:173], v[210:213], v[44:47]
	v_mfma_f32_16x16x32_bf16 v[40:43], v[178:181], v[210:213], v[40:43]
	v_mfma_f32_16x16x32_bf16 v[36:39], v[170:173], v[218:221], v[36:39]
	v_mfma_f32_16x16x32_bf16 v[32:35], v[178:181], v[218:221], v[32:35]
	s_setprio 0
	s_barrier
; #define PG8_STAGE(bufoff, gbase, voff) do { _Pragma("unroll") for (int _i = 0; _i < 2; ++_i) \
;         __builtin_amdgcn_global_load_lds((const unsigned*)((const char*)(gbase) + (voff)[_i]), (PG8_LAS unsigned*)(lds + (bufoff) + ldsw + _i * 8192), 16, 0, 0); } while (0)
; #define PG8_LDA(dst, b, h) do { _Pragma("unroll") for (int m = 0; m < 4; ++m) _Pragma("unroll") for (int k = 0; k < 2; ++k) dst[m][k] = *(const PG8_LAS bf16x8*)(lds + PG8_SA(b, h) + aoff + m * 2048 + k * 1024); } while (0)
; #define PG8_MMA(ai, bj, At, Bt) do { __builtin_amdgcn_s_setprio(1); _Pragma("unroll") for (int m = 0; m < 4; ++m) _Pragma("unroll") for (int n = 0; n < 2; ++n) _Pragma("unroll") for (int k = 0; k < 2; ++k) \
;         acc[ai][bj][m][n] = __builtin_amdgcn_mfma_f32_16x16x32_bf16(Bt[n][k], At[m][k], acc[ai][bj][m][n], 0, 0, 0); __builtin_amdgcn_s_setprio(0); } while (0)
; #define PG8_WAIT_V(n) asm volatile("s_waitcnt vmcnt(" #n ")" ::: "memory")
; #define PG8_WAIT_L(n) asm volatile("s_waitcnt lgkmcnt(" #n ")" ::: "memory")
; #define PG8_BAR __builtin_amdgcn_s_barrier()
; #define PG8_SCHED __builtin_amdgcn_sched_barrier(0)
; template <class Epi, class Sched, bool ALIGN_EPI = false, bool SP2 = false>
; __device__ __forceinline__ void gemm_phase(PG8_LAS unsigned char* lds, const Gemm g, const Sched& S, const Epi& E) {
;     ...
;             PG8_LDA(At, 1, 1); PG8_STAGE(PG8_SB(1, 0), b3, voffB); PG8_STAGE(PG8_SB(1, 1), b3 + hstep, voffB); PG8_STAGE(PG8_SA(1, 0), a3, voffA);
;             PG8_WAIT_V(8); PG8_WAIT_L(0); PG8_BAR; PG8_MMA(1, 0, At, B0); PG8_MMA(1, 1, At, B1); PG8_BAR; PG8_SCHED;
	s_add_i32 s3, s3, s52
	v_lshl_add_u64 v[222:223], v[222:223], 0, s[16:17]
	s_mov_b32 m0, s3
	ds_read_b128 v[190:193], v149 offset:49152
	ds_read_b128 v[194:197], v233 offset:49152
	ds_read_b128 v[198:201], v149 offset:51200
	ds_read_b128 v[202:205], v233 offset:51200
	ds_read_b128 v[206:209], v149 offset:53248
	ds_read_b128 v[210:213], v233 offset:53248
	ds_read_b128 v[214:217], v149 offset:55296
	ds_read_b128 v[218:221], v233 offset:55296
	global_load_lds_dwordx4 v[222:223], off
	s_add_i32 m0, s3, 0x2000
	s_add_u32 s10, s36, 0xb0080
	v_lshl_add_u64 v[222:223], v[224:225], 0, s[16:17]
	s_addc_u32 s11, s37, 0
	s_add_i32 s3, s30, s52
	global_load_lds_dwordx4 v[222:223], off
	v_lshl_add_u64 v[222:223], s[10:11], 0, v[130:131]
	s_mov_b32 m0, s3
	s_nop 0
	global_load_lds_dwordx4 v[222:223], off
	v_lshl_add_u64 v[222:223], s[10:11], 0, v[134:135]
	s_add_i32 m0, s3, 0x2000
	s_nop 0
	global_load_lds_dwordx4 v[222:223], off
	v_lshl_add_u64 v[222:223], v[226:227], 0, s[16:17]
	s_mov_b32 m0, s58
	s_nop 0
	global_load_lds_dwordx4 v[222:223], off
	v_lshl_add_u64 v[222:223], v[228:229], 0, s[16:17]
	s_mov_b32 m0, s59
	s_nop 0
	global_load_lds_dwordx4 v[222:223], off
	s_waitcnt vmcnt(8)
	s_waitcnt lgkmcnt(0)
	s_barrier
	s_setprio 1
	s_waitcnt lgkmcnt(0)
	v_mfma_f32_16x16x32_bf16 v[92:95], v[150:153], v[190:193], v[92:95]
	v_mfma_f32_16x16x32_bf16 v[88:91], v[158:161], v[190:193], v[88:91]
	v_mfma_f32_16x16x32_bf16 v[84:87], v[150:153], v[198:201], v[84:87]
	v_mfma_f32_16x16x32_bf16 v[80:83], v[158:161], v[198:201], v[80:83]
	v_mfma_f32_16x16x32_bf16 v[72:75], v[150:153], v[206:209], v[72:75]
	v_mfma_f32_16x16x32_bf16 v[64:67], v[158:161], v[206:209], v[64:67]
	v_mfma_f32_16x16x32_bf16 v[56:59], v[150:153], v[214:217], v[56:59]
	v_mfma_f32_16x16x32_bf16 v[48:51], v[158:161], v[214:217], v[48:51]
	v_mfma_f32_16x16x32_bf16 v[92:95], v[154:157], v[194:197], v[92:95]
	v_mfma_f32_16x16x32_bf16 v[88:91], v[162:165], v[194:197], v[88:91]
	v_mfma_f32_16x16x32_bf16 v[84:87], v[154:157], v[202:205], v[84:87]
	v_mfma_f32_16x16x32_bf16 v[80:83], v[162:165], v[202:205], v[80:83]
	v_mfma_f32_16x16x32_bf16 v[72:75], v[154:157], v[210:213], v[72:75]
	v_mfma_f32_16x16x32_bf16 v[64:67], v[162:165], v[210:213], v[64:67]
	v_mfma_f32_16x16x32_bf16 v[56:59], v[154:157], v[218:221], v[56:59]
	v_mfma_f32_16x16x32_bf16 v[48:51], v[162:165], v[218:221], v[48:51]
	s_setprio 0
	s_setprio 1
	v_mfma_f32_16x16x32_bf16 v[28:31], v[166:169], v[190:193], v[28:31]
	v_mfma_f32_16x16x32_bf16 v[24:27], v[174:177], v[190:193], v[24:27]
	v_mfma_f32_16x16x32_bf16 v[20:23], v[166:169], v[198:201], v[20:23]
	v_mfma_f32_16x16x32_bf16 v[16:19], v[174:177], v[198:201], v[16:19]
	v_mfma_f32_16x16x32_bf16 v[12:15], v[166:169], v[206:209], v[12:15]
	v_mfma_f32_16x16x32_bf16 v[8:11], v[174:177], v[206:209], v[8:11]
	v_mfma_f32_16x16x32_bf16 v[4:7], v[166:169], v[214:217], v[4:7]
	v_mfma_f32_16x16x32_bf16 v[0:3], v[174:177], v[214:217], v[0:3]
	v_mfma_f32_16x16x32_bf16 v[28:31], v[170:173], v[194:197], v[28:31]
	v_mfma_f32_16x16x32_bf16 v[24:27], v[178:181], v[194:197], v[24:27]
	v_mfma_f32_16x16x32_bf16 v[20:23], v[170:173], v[202:205], v[20:23]
	v_mfma_f32_16x16x32_bf16 v[16:19], v[178:181], v[202:205], v[16:19]
	v_mfma_f32_16x16x32_bf16 v[12:15], v[170:173], v[210:213], v[12:15]
	v_mfma_f32_16x16x32_bf16 v[8:11], v[178:181], v[210:213], v[8:11]
	v_mfma_f32_16x16x32_bf16 v[4:7], v[170:173], v[218:221], v[4:7]
	v_mfma_f32_16x16x32_bf16 v[0:3], v[178:181], v[218:221], v[0:3]
	s_setprio 0
	s_barrier
	s_add_i32 s74, s74, 2
	s_add_u32 s72, s72, 0x100
	s_addc_u32 s73, s73, 0
	s_cmp_gt_u32 s74, 41
	s_mov_b64 s[30:31], s[34:35]
	s_cbranch_scc0 .LBB0_303
	s_and_b64 vcc, exec, s[18:19]
	s_cbranch_vccz .LBB0_306
	s_barrier
